# stack + counted lgkmcnt waits for the V fragment reads of the PV section (each MFMA waits only for its own fragment)
# speedup vs baseline: 1.0077x; 1.0075x over previous
.LBB0_887:
	v_lshl_add_u32 v203, s68, 6, v202
	v_exp_f32_e32 v209, v80
	v_exp_f32_e32 v211, v81
	v_exp_f32_e32 v213, v82
	v_exp_f32_e32 v215, v83
	ds_read_b128 v[80:83], v203 offset:13312
	ds_read_b128 v[204:207], v203 offset:17920
	v_exp_f32_e32 v217, v84
	v_exp_f32_e32 v219, v85
	v_exp_f32_e32 v221, v86
	v_exp_f32_e32 v223, v87
	v_exp_f32_e32 v208, v64
	v_exp_f32_e32 v210, v65
	v_exp_f32_e32 v212, v66
	v_exp_f32_e32 v214, v67
	v_exp_f32_e32 v216, v68
	v_exp_f32_e32 v218, v69
	v_exp_f32_e32 v220, v70
	v_exp_f32_e32 v222, v71
	v_cvt_pk_bf16_f32 v64, v209, v211
	v_cvt_pk_bf16_f32 v65, v213, v215
	v_cvt_pk_bf16_f32 v66, v217, v219
	v_cvt_pk_bf16_f32 v67, v221, v223
	v_cvt_pk_bf16_f32 v68, v208, v210
	v_cvt_pk_bf16_f32 v69, v212, v214
	v_cvt_pk_bf16_f32 v70, v216, v218
	v_cvt_pk_bf16_f32 v71, v220, v222
	ds_read_b128 v[84:87], v203 offset:13344
	s_waitcnt lgkmcnt(2)
	v_mfma_f32_32x32x16_bf16 v[48:63], v[80:83], v[64:67], v[48:63]
	v_exp_f32_e32 v225, v88
	v_exp_f32_e32 v224, v72
	v_exp_f32_e32 v88, v73
	v_exp_f32_e32 v89, v89
	v_exp_f32_e32 v227, v90
	v_exp_f32_e32 v91, v91
	v_exp_f32_e32 v229, v92
	v_mfma_f32_32x32x16_bf16 v[16:31], v[80:83], v[68:71], v[16:31]
	ds_read_b128 v[80:83], v203 offset:17952
	v_exp_f32_e32 v93, v93
	v_exp_f32_e32 v231, v94
	v_exp_f32_e32 v95, v95
	v_exp_f32_e32 v226, v74
	v_exp_f32_e32 v90, v75
	v_exp_f32_e32 v228, v76
	s_waitcnt lgkmcnt(2)
	v_mfma_f32_32x32x16_bf16 v[32:47], v[204:207], v[64:67], v[32:47]
	v_exp_f32_e32 v92, v77
	v_add_f32_e32 v64, v210, v208
	v_add_f32_e32 v65, v211, v209
	v_exp_f32_e32 v230, v78
	v_add_f32_e32 v208, v212, v64
	v_add_f32_e32 v209, v213, v65
	v_exp_f32_e32 v94, v79
	v_add_f32_e32 v72, v214, v208
	v_add_f32_e32 v73, v215, v209
	v_mfma_f32_32x32x16_bf16 v[0:15], v[204:207], v[68:71], v[0:15]
	v_add_f32_e64 v72, v216, v72
	v_add_f32_e64 v73, v217, v73
	v_cvt_pk_bf16_f32 v64, v225, v89
	v_add_f32_e64 v72, v218, v72
	v_add_f32_e64 v73, v219, v73
	v_cvt_pk_bf16_f32 v65, v227, v91
	v_add_f32_e32 v72, v220, v72
	v_add_f32_e32 v73, v221, v73
	v_cvt_pk_bf16_f32 v66, v229, v93
	v_add_f32_e32 v72, v222, v72
	v_add_f32_e32 v73, v223, v73
	v_cvt_pk_bf16_f32 v67, v231, v95
	v_cvt_pk_bf16_f32 v68, v224, v88
	v_cvt_pk_bf16_f32 v69, v226, v90
	v_cvt_pk_bf16_f32 v70, v228, v92
	v_cvt_pk_bf16_f32 v71, v230, v94
	v_add_f32_e32 v72, v224, v72
	v_add_f32_e32 v73, v225, v73
	s_waitcnt lgkmcnt(1)
	v_mfma_f32_32x32x16_bf16 v[48:63], v[84:87], v[64:67], v[48:63]
	v_add_f32_e64 v72, v88, v72
	v_add_f32_e64 v73, v89, v73
	s_xor_b64 s[28:29], s[66:67], -1
	s_mov_b32 s68, 1
	s_mov_b64 s[66:67], 0
	s_and_b64 vcc, exec, s[28:29]
	v_mfma_f32_32x32x16_bf16 v[16:31], v[84:87], v[68:71], v[16:31]
	s_waitcnt lgkmcnt(0)
	v_mfma_f32_32x32x16_bf16 v[32:47], v[80:83], v[64:67], v[32:47]
	v_add_f32_e64 v64, v226, v72
	v_add_f32_e64 v65, v227, v73
	v_add_f32_e64 v64, v90, v64
	v_add_f32_e64 v65, v91, v65
	v_add_f32_e64 v64, v228, v64
	v_add_f32_e64 v65, v229, v65
	v_add_f32_e32 v64, v92, v64
	v_add_f32_e32 v65, v93, v65
	v_mfma_f32_32x32x16_bf16 v[0:15], v[80:83], v[68:71], v[0:15]
	v_add_f32_e64 v64, v230, v64
	v_add_f32_e64 v65, v231, v65
	v_add_f32_e64 v64, v94, v64
	v_add_f32_e64 v65, v95, v65
	v_add_f32_e64 v150, v150, v64
	v_add_f32_e64 v151, v151, v65
	s_cbranch_vccnz .LBB0_889
	s_mov_b64 s[64:65], 0
	s_and_b64 vcc, exec, s[62:63]
	v_lshl_or_b32 v203, s68, 5, v190
	s_mov_b64 s[28:29], -1
	s_cbranch_vccz .LBB0_882
	s_branch .LBB0_883

.LBB0_2121:
	v_lshl_add_u32 v203, s68, 6, v202
	v_exp_f32_e32 v209, v80
	v_exp_f32_e32 v211, v81
	v_exp_f32_e32 v213, v82
	v_exp_f32_e32 v215, v83
	ds_read_b128 v[80:83], v203 offset:13312
	ds_read_b128 v[204:207], v203 offset:17920
	v_exp_f32_e32 v217, v84
	v_exp_f32_e32 v219, v85
	v_exp_f32_e32 v221, v86
	v_exp_f32_e32 v223, v87
	v_exp_f32_e32 v208, v64
	v_exp_f32_e32 v210, v65
	v_exp_f32_e32 v212, v66
	v_exp_f32_e32 v214, v67
	v_exp_f32_e32 v216, v68
	v_exp_f32_e32 v218, v69
	v_exp_f32_e32 v220, v70
	v_exp_f32_e32 v222, v71
	v_cvt_pk_bf16_f32 v64, v209, v211
	v_cvt_pk_bf16_f32 v65, v213, v215
	v_cvt_pk_bf16_f32 v66, v217, v219
	v_cvt_pk_bf16_f32 v67, v221, v223
	v_cvt_pk_bf16_f32 v68, v208, v210
	v_cvt_pk_bf16_f32 v69, v212, v214
	v_cvt_pk_bf16_f32 v70, v216, v218
	v_cvt_pk_bf16_f32 v71, v220, v222
	ds_read_b128 v[84:87], v203 offset:13344
	s_waitcnt lgkmcnt(2)
	v_mfma_f32_32x32x16_bf16 v[48:63], v[80:83], v[64:67], v[48:63]
	v_exp_f32_e32 v225, v88
	v_exp_f32_e32 v224, v72
	v_exp_f32_e32 v88, v73
	v_exp_f32_e32 v89, v89
	v_exp_f32_e32 v227, v90
	v_exp_f32_e32 v91, v91
	v_exp_f32_e32 v229, v92
	v_mfma_f32_32x32x16_bf16 v[16:31], v[80:83], v[68:71], v[16:31]
	ds_read_b128 v[80:83], v203 offset:17952
	v_exp_f32_e32 v93, v93
	v_exp_f32_e32 v231, v94
	v_exp_f32_e32 v95, v95
	v_exp_f32_e32 v226, v74
	v_exp_f32_e32 v90, v75
	v_exp_f32_e32 v228, v76
	s_waitcnt lgkmcnt(2)
	v_mfma_f32_32x32x16_bf16 v[32:47], v[204:207], v[64:67], v[32:47]
	v_exp_f32_e32 v92, v77
	v_add_f32_e32 v64, v210, v208
	v_add_f32_e32 v65, v211, v209
	v_exp_f32_e32 v230, v78
	v_add_f32_e32 v208, v212, v64
	v_add_f32_e32 v209, v213, v65
	v_exp_f32_e32 v94, v79
	v_add_f32_e32 v72, v214, v208
	v_add_f32_e32 v73, v215, v209
	v_mfma_f32_32x32x16_bf16 v[0:15], v[204:207], v[68:71], v[0:15]
	v_add_f32_e64 v72, v216, v72
	v_add_f32_e64 v73, v217, v73
	v_cvt_pk_bf16_f32 v64, v225, v89
	v_add_f32_e64 v72, v218, v72
	v_add_f32_e64 v73, v219, v73
	v_cvt_pk_bf16_f32 v65, v227, v91
	v_add_f32_e32 v72, v220, v72
	v_add_f32_e32 v73, v221, v73
	v_cvt_pk_bf16_f32 v66, v229, v93
	v_add_f32_e32 v72, v222, v72
	v_add_f32_e32 v73, v223, v73
	v_cvt_pk_bf16_f32 v67, v231, v95
	v_cvt_pk_bf16_f32 v68, v224, v88
	v_cvt_pk_bf16_f32 v69, v226, v90
	v_cvt_pk_bf16_f32 v70, v228, v92
	v_cvt_pk_bf16_f32 v71, v230, v94
	v_add_f32_e32 v72, v224, v72
	v_add_f32_e32 v73, v225, v73
	s_waitcnt lgkmcnt(1)
	v_mfma_f32_32x32x16_bf16 v[48:63], v[84:87], v[64:67], v[48:63]
	v_add_f32_e64 v72, v88, v72
	v_add_f32_e64 v73, v89, v73
	s_xor_b64 s[34:35], s[66:67], -1
	s_mov_b32 s68, 1
	s_mov_b64 s[66:67], 0
	s_and_b64 vcc, exec, s[34:35]
	v_mfma_f32_32x32x16_bf16 v[16:31], v[84:87], v[68:71], v[16:31]
	s_waitcnt lgkmcnt(0)
	v_mfma_f32_32x32x16_bf16 v[32:47], v[80:83], v[64:67], v[32:47]
	v_add_f32_e64 v64, v226, v72
	v_add_f32_e64 v65, v227, v73
	v_add_f32_e64 v64, v90, v64
	v_add_f32_e64 v65, v91, v65
	v_add_f32_e64 v64, v228, v64
	v_add_f32_e64 v65, v229, v65
	v_add_f32_e32 v64, v92, v64
	v_add_f32_e32 v65, v93, v65
	v_mfma_f32_32x32x16_bf16 v[0:15], v[80:83], v[68:71], v[0:15]
	v_add_f32_e64 v64, v230, v64
	v_add_f32_e64 v65, v231, v65
	v_add_f32_e64 v64, v94, v64
	v_add_f32_e64 v65, v95, v65
	v_add_f32_e64 v150, v150, v64
	v_add_f32_e64 v151, v151, v65
	s_cbranch_vccnz .LBB0_2123
	s_mov_b64 s[64:65], 0
	s_and_b64 vcc, exec, s[62:63]
	v_lshl_or_b32 v203, s68, 5, v190
	s_mov_b64 s[34:35], -1
	s_cbranch_vccz .LBB0_2116
	s_branch .LBB0_2117
